# attention loop: waves 4-7 run at priority 1 for the first 8 MFMAs of every tile step (older half no longer idles at tile barrier)
# baseline (speedup 1.0000x reference)
.LBB0_436:
	v_readlane_b32 s0, v248, 10
	v_readlane_b32 s1, v248, 11
	s_cmp_lt_i32 s0, 3
	s_cselect_b64 s[0:1], -1, 0
	s_and_b64 s[0:1], s[0:1], s[2:3]
	s_andn2_b64 vcc, exec, s[0:1]
	s_cbranch_vccnz .LBB0_525
	v_readfirstlane_b32 s100, v161
	s_lshr_b32 s100, s100, 8
	v_lshlrev_b32_e32 v0, 2, v160
	global_load_dword v4, v0, s[24:25]
	global_load_dword v5, v0, s[24:25] offset:256
	s_waitcnt lgkmcnt(0)
	global_load_dword v6, v0, s[24:25] offset:512
	global_load_dword v7, v0, s[24:25] offset:768
	v_mbcnt_lo_u32_b32 v1, -1, 0
	v_mbcnt_hi_u32_b32 v8, -1, v1
	v_and_b32_e32 v9, 64, v8
	v_xor_b32_e32 v10, 1, v8
	v_add_u32_e32 v9, 64, v9
	v_cmp_lt_i32_e32 vcc, v10, v9
	v_xor_b32_e32 v11, 2, v8
	v_xor_b32_e32 v12, 4, v8
	v_cndmask_b32_e32 v10, v8, v10, vcc
	v_lshlrev_b32_e32 v10, 2, v10
	v_cmp_lt_i32_e32 vcc, v11, v9
	v_xor_b32_e32 v13, 8, v8
	v_xor_b32_e32 v14, 16, v8
	v_cndmask_b32_e32 v11, v8, v11, vcc
	v_lshlrev_b32_e32 v11, 2, v11
	v_cmp_lt_i32_e32 vcc, v12, v9
	v_xor_b32_e32 v15, 32, v8
	v_lshrrev_b32_e32 v0, 5, v160
	v_bfe_u32 v3, v161, 1, 3
	v_writelane_b32 v248, s0, 27
	s_cmpk_lt_i32 s15, 0xc00
	v_bitop3_b32 v1, v0, v3, 2 bitop3:0x36
	v_bitop3_b32 v2, v0, v3, 4 bitop3:0x36
	v_bitop3_b32 v3, v0, v3, 6 bitop3:0x36
	v_and_b32_e32 v212, 31, v161
	v_lshrrev_b32_e32 v210, 3, v160
	v_and_b32_e32 v211, 7, v161
	v_lshlrev_b32_e32 v148, 3, v0
	v_writelane_b32 v248, s1, 28
	s_waitcnt vmcnt(2)
	v_mul_f32_e32 v16, v4, v5
	ds_bpermute_b32 v16, v10, v16
	s_waitcnt vmcnt(0)
	v_mul_f32_e32 v17, v6, v7
	ds_bpermute_b32 v10, v10, v17
	s_waitcnt lgkmcnt(1)
	v_fmac_f32_e32 v16, v4, v5
	ds_bpermute_b32 v4, v11, v16
	s_waitcnt lgkmcnt(1)
	v_fmac_f32_e32 v10, v6, v7
	ds_bpermute_b32 v5, v11, v10
	v_cndmask_b32_e32 v6, v8, v12, vcc
	v_lshlrev_b32_e32 v6, 2, v6
	s_waitcnt lgkmcnt(1)
	v_add_f32_e32 v4, v16, v4
	ds_bpermute_b32 v7, v6, v4
	s_waitcnt lgkmcnt(1)
	v_add_f32_e32 v5, v10, v5
	ds_bpermute_b32 v6, v6, v5
	v_cmp_lt_i32_e32 vcc, v13, v9
	s_waitcnt lgkmcnt(1)
	v_add_f32_e32 v4, v4, v7
	v_cndmask_b32_e32 v10, v8, v13, vcc
	v_lshlrev_b32_e32 v10, 2, v10
	s_waitcnt lgkmcnt(0)
	v_add_f32_e32 v5, v5, v6
	ds_bpermute_b32 v6, v10, v4
	ds_bpermute_b32 v7, v10, v5
	v_cmp_lt_i32_e32 vcc, v14, v9
	s_waitcnt lgkmcnt(1)
	v_add_f32_e32 v4, v4, v6
	v_cndmask_b32_e32 v10, v8, v14, vcc
	v_lshlrev_b32_e32 v10, 2, v10
	s_waitcnt lgkmcnt(0)
	v_add_f32_e32 v5, v5, v7
	ds_bpermute_b32 v6, v10, v4
	ds_bpermute_b32 v7, v10, v5
	v_cmp_lt_i32_e32 vcc, v15, v9
	s_waitcnt lgkmcnt(1)
	v_add_f32_e32 v6, v4, v6
	v_cndmask_b32_e32 v8, v8, v15, vcc
	v_lshlrev_b32_e32 v9, 2, v8
	s_waitcnt lgkmcnt(0)
	v_add_f32_e32 v7, v5, v7
	ds_bpermute_b32 v8, v9, v6
	ds_bpermute_b32 v9, v9, v7
	v_lshrrev_b32_e32 v4, 4, v160
	s_cbranch_scc1 .LBB0_439
	v_lshrrev_b32_e32 v5, 1, v161
	v_bitop3_b32 v5, v0, v5, 7 bitop3:0x78
	v_and_b32_e32 v162, 31, v161
	v_bitop3_b32 v10, v4, v161, 7 bitop3:0x78
	s_lshl_b32 s0, s88, 14
	v_lshlrev_b32_e32 v149, 4, v5
	v_lshlrev_b32_e32 v208, 4, v1
	v_lshlrev_b32_e32 v209, 4, v2
	v_lshlrev_b32_e32 v226, 4, v3
	v_lshlrev_b32_e32 v213, 7, v162
	v_lshrrev_b32_e32 v164, 3, v160
	v_and_b32_e32 v5, 7, v161
	v_lshlrev_b32_e32 v146, 3, v10
	v_mov_b32_e32 v147, 0
	v_lshlrev_b32_e32 v169, 3, v0
	s_mov_b64 s[2:3], 0
	s_branch .LBB0_440

.LBB0_458:
	s_add_i32 s78, s34, -4
	s_cmp_gt_i32 s78, s39
	s_cselect_b64 s[82:83], -1, 0
	v_cndmask_b32_e64 v200, v201, -v201, s[82:83]
	s_and_b64 s[82:83], s[82:83], exec
	s_cselect_b32 s82, s63, s60
	s_ashr_i32 s83, s82, 31
	s_lshl_b64 s[84:85], s[82:83], 1
	s_addk_i32 s80, 0xc000
	s_cmp_lg_u32 s10, 0
	s_cselect_b32 s80, s80, 0x8000
	s_add_i32 s80, s14, s80
	v_lshl_add_u64 v[98:99], v[204:205], 0, s[84:85]
	s_add_i32 m0, s80, 0xc000
	v_lshl_add_u64 v[100:101], v[206:207], 0, s[84:85]
	global_load_lds_dwordx4 v[98:99], off
	s_add_i32 m0, s80, 0xc400
	v_cvt_f32_i32_e32 v98, s82
	global_load_lds_dwordx4 v[100:101], off
	v_add_u32_e32 v183, s79, v218
	v_add_f32_e32 v98, v155, v98
	v_fma_f32 v224, v200, v98, -v199
	v_fma_f32 v98, 0, v200, v224
	v_add_f32_e32 v99, v200, v224
	v_fma_f32 v100, v200, s64, v224
	v_fma_f32 v101, v200, s65, v224
	v_fma_f32 v102, v200, s66, v224
	v_fma_f32 v103, v200, s67, v224
	v_mul_f32_e32 v240, 0x42000000, v200
	ds_read_b128 v[228:231], v181 offset:53248
	s_waitcnt lgkmcnt(3)
	v_mfma_f32_32x32x16_bf16 v[18:33], v[126:129], v[106:109], v[18:33]
	v_add_f32_e32 v254, v70, v254
	v_add_f32_e32 v254, v252, v254
	v_exp_f32_e32 v71, v71
	v_fma_f32 v104, v200, s68, v224
	v_fma_f32 v105, v200, s69, v224
	ds_read_b128 v[126:129], v181 offset:57344
	s_waitcnt lgkmcnt(3)
	v_mfma_f32_32x32x16_bf16 v[2:17], v[118:121], v[106:109], v[2:17]
	s_setprio 0
	v_add_f32_e32 v254, v71, v254
	v_exp_f32_e32 v253, v87
	v_exp_f32_e32 v82, v72
	ds_read_b128 v[118:121], v181 offset:61440
	s_waitcnt lgkmcnt(3)
	v_mfma_f32_32x32x16_bf16 v[50:65], v[122:125], v[110:113], v[50:65]
	v_add_f32_e32 v254, v253, v254
	v_add_f32_e32 v254, v82, v254
	v_exp_f32_e32 v72, v88
	v_fma_f32 v106, v200, s70, v224
	v_fma_f32 v107, v200, s71, v224
	v_add_u32_e32 v179, v179, v226
	ds_read_b128 v[122:125], v179 offset:49152
	s_waitcnt lgkmcnt(3)
	v_mfma_f32_32x32x16_bf16 v[34:49], v[228:231], v[110:113], v[34:49]
	v_add_f32_e32 v254, v72, v254
	v_exp_f32_e32 v83, v73
	v_exp_f32_e32 v73, v89
	ds_read_b128 v[228:231], v179 offset:53248
	s_waitcnt lgkmcnt(3)
	v_mfma_f32_32x32x16_bf16 v[18:33], v[126:129], v[110:113], v[18:33]
	v_add_f32_e32 v254, v83, v254
	v_add_f32_e32 v254, v73, v254
	v_exp_f32_e32 v74, v74
	v_fma_f32 v108, v200, s72, v224
	v_fma_f32 v109, v200, s73, v224
	ds_read_b128 v[126:129], v179 offset:57344
	s_waitcnt lgkmcnt(3)
	v_mfma_f32_32x32x16_bf16 v[2:17], v[118:121], v[110:113], v[2:17]
	v_add_f32_e32 v254, v74, v254
	v_exp_f32_e32 v90, v90
	v_exp_f32_e32 v75, v75
	ds_read_b128 v[118:121], v179 offset:61440
	s_waitcnt lgkmcnt(3)
	v_mfma_f32_32x32x16_bf16 v[50:65], v[122:125], v[114:117], v[50:65]
	v_add_f32_e32 v254, v90, v254
	v_add_f32_e32 v254, v75, v254
	v_exp_f32_e32 v91, v91
	v_fma_f32 v110, v200, s74, v224
	v_fma_f32 v111, v200, s75, v224
	v_add_u32_e32 v112, v183, v149
	ds_read_b128 v[232:235], v112
	s_waitcnt lgkmcnt(3)
	v_mfma_f32_32x32x16_bf16 v[34:49], v[228:231], v[114:117], v[34:49]
	v_add_f32_e32 v254, v91, v254
	v_exp_f32_e32 v76, v76
	v_exp_f32_e32 v92, v92
	ds_read_b128 v[228:231], v112 offset:4096
	s_waitcnt lgkmcnt(3)
	v_mfma_f32_32x32x16_bf16 v[18:33], v[126:129], v[114:117], v[18:33]
	v_add_f32_e32 v254, v76, v254
	v_add_f32_e32 v254, v92, v254
	v_exp_f32_e32 v77, v77
	v_fma_f32 v112, v200, s76, v224
	v_fma_f32 v113, v200, s77, v224
	v_add_u32_e32 v179, v183, v208
	ds_read_b128 v[236:239], v179
	s_waitcnt lgkmcnt(3)
	v_mfma_f32_32x32x16_bf16 v[2:17], v[118:121], v[114:117], v[2:17]
	v_add_f32_e64 v114, v240, v98
	v_add_f32_e64 v115, v240, v99
	v_add_f32_e64 v128, v240, v112
	v_add_f32_e64 v129, v240, v113
	v_add_f32_e64 v126, v240, v110
	v_add_f32_e64 v127, v240, v111
	v_add_f32_e32 v124, v240, v108
	v_add_f32_e32 v125, v240, v109
	v_add_f32_e32 v122, v240, v106
	v_add_f32_e32 v123, v240, v107
	v_add_f32_e32 v120, v240, v104
	v_add_f32_e32 v121, v240, v105
	v_add_f32_e32 v118, v240, v102
	v_add_f32_e32 v119, v240, v103
	v_add_f32_e32 v116, v240, v100
	v_add_f32_e32 v117, v240, v101
	ds_read_b128 v[240:243], v179 offset:4096
	s_waitcnt lgkmcnt(3)
	v_mfma_f32_32x32x16_bf16 v[98:113], v[232:235], v[130:133], v[98:113]
	v_add_f32_e32 v254, v77, v254
	v_exp_f32_e32 v93, v93
	v_exp_f32_e32 v78, v78
	v_add_u32_e32 v179, v183, v209
	ds_read_b128 v[232:235], v179
	s_waitcnt lgkmcnt(3)
	v_mfma_f32_32x32x16_bf16 v[114:129], v[228:231], v[130:133], v[114:129]
	v_add_f32_e32 v254, v93, v254
	v_add_f32_e32 v254, v78, v254
	v_exp_f32_e32 v94, v94
	v_exp_f32_e32 v79, v79
	ds_read_b128 v[228:231], v179 offset:4096
	s_waitcnt lgkmcnt(3)
	v_mfma_f32_32x32x16_bf16 v[98:113], v[236:239], v[134:137], v[98:113]
	v_add_f32_e32 v254, v94, v254
	v_add_f32_e32 v254, v79, v254
	v_exp_f32_e32 v95, v95
	v_exp_f32_e32 v80, v80
	v_add_u32_e32 v179, v183, v226
	ds_read_b128 v[236:239], v179
	s_waitcnt lgkmcnt(3)
	v_mfma_f32_32x32x16_bf16 v[114:129], v[240:243], v[134:137], v[114:129]
	v_add_f32_e32 v254, v95, v254
	v_add_f32_e32 v254, v80, v254
	v_exp_f32_e32 v96, v96
	v_exp_f32_e32 v81, v81
	ds_read_b128 v[240:243], v179 offset:4096
	s_waitcnt lgkmcnt(3)
	v_mfma_f32_32x32x16_bf16 v[98:113], v[232:235], v[138:141], v[98:113]
	v_add_f32_e32 v254, v96, v254
	v_add_f32_e32 v254, v81, v254
	v_exp_f32_e32 v97, v97
	s_waitcnt lgkmcnt(2)
	v_mfma_f32_32x32x16_bf16 v[114:129], v[228:231], v[138:141], v[114:129]
	v_add_f32_e32 v254, v97, v254
	s_waitcnt lgkmcnt(1)
	v_mfma_f32_32x32x16_bf16 v[98:113], v[236:239], v[142:145], v[98:113]
	s_waitcnt lgkmcnt(0)
	v_mfma_f32_32x32x16_bf16 v[114:129], v[240:243], v[142:145], v[114:129]
	s_andn2_b64 vcc, exec, s[4:5]
	s_mov_b64 s[4:5], -1
	s_cbranch_vccz .LBB0_470
	s_andn2_b64 vcc, exec, s[4:5]
	s_cbranch_vccz .LBB0_471

.LBB0_466:
	s_cmp_lt_i32 s78, s39
	s_cselect_b64 s[80:81], -1, 0
	v_cndmask_b32_e64 v228, -v201, v201, s[80:81]
	s_and_b64 s[80:81], s[80:81], exec
	s_cselect_b32 s60, s78, s61
	s_add_i32 s60, s60, s33
	s_lshl_b32 s78, s60, 6
	s_ashr_i32 s79, s78, 31
	s_lshl_b64 s[80:81], s[78:79], 1
	s_addk_i32 s62, 0xc000
	s_cmp_lg_u32 s5, 0
	s_cselect_b32 s60, s62, 0x8000
	s_add_i32 s60, s14, s60
	v_lshl_add_u64 v[66:67], v[204:205], 0, s[80:81]
	s_add_i32 m0, s60, 0xc000
	v_lshl_add_u64 v[68:69], v[206:207], 0, s[80:81]
	global_load_lds_dwordx4 v[66:67], off
	s_add_i32 m0, s60, 0xc400
	v_cvt_f32_i32_e32 v66, s78
	global_load_lds_dwordx4 v[68:69], off
	v_exp_f32_e32 v231, v98
	v_add_f32_e32 v66, v155, v66
	v_fma_f32 v230, v228, v66, -v199
	v_add_u32_e32 v229, s10, v218
	v_exp_f32_e32 v233, v114
	v_fma_f32 v66, 0, v228, v230
	v_exp_f32_e32 v234, v99
	v_exp_f32_e32 v235, v115
	v_add_f32_e32 v67, v228, v230
	v_exp_f32_e32 v236, v100
	v_exp_f32_e32 v237, v116
	v_exp_f32_e32 v238, v101
	v_exp_f32_e32 v239, v117
	v_fma_f32 v68, v228, s64, v230
	v_fma_f32 v69, v228, s65, v230
	v_fma_f32 v70, v228, s66, v230
	v_fma_f32 v71, v228, s67, v230
	v_cvt_pk_bf16_f32 v98, v249, v250
	v_cvt_pk_bf16_f32 v99, v195, v251
	v_cvt_pk_bf16_f32 v100, v252, v253
	v_cvt_pk_bf16_f32 v101, v72, v73
	v_cvt_pk_bf16_f32 v114, v90, v91
	v_cvt_pk_bf16_f32 v115, v92, v93
	v_cvt_pk_bf16_f32 v116, v94, v95
	v_cvt_pk_bf16_f32 v117, v96, v97
	v_mul_f32_e32 v232, 0x42000000, v228
	v_exp_f32_e32 v240, v102
	v_exp_f32_e32 v241, v118
	v_exp_f32_e32 v242, v103
	v_exp_f32_e32 v243, v119
	ds_read_b128 v[90:93], v227 offset:53248
	s_waitcnt lgkmcnt(3)
	v_mfma_f32_32x32x16_bf16 v[18:33], v[86:89], v[74:77], v[18:33]
	v_add_f32_e32 v254, 0, v231
	v_add_f32_e32 v254, v233, v254
	v_fma_f32 v72, v228, s68, v230
	v_fma_f32 v73, v228, s69, v230
	v_exp_f32_e32 v181, v104
	v_exp_f32_e32 v183, v120
	ds_read_b128 v[86:89], v227 offset:57344
	s_waitcnt lgkmcnt(3)
	v_mfma_f32_32x32x16_bf16 v[2:17], v[82:85], v[74:77], v[2:17]
	s_setprio 0
	v_add_f32_e32 v254, v234, v254
	v_add_f32_e32 v254, v235, v254
	v_exp_f32_e32 v195, v105
	v_exp_f32_e32 v200, v121
	ds_read_b128 v[82:85], v227 offset:61440
	s_waitcnt lgkmcnt(3)
	v_mfma_f32_32x32x16_bf16 v[50:65], v[78:81], v[98:101], v[50:65]
	v_add_f32_e32 v254, v236, v254
	v_add_f32_e32 v254, v237, v254
	v_fma_f32 v74, v228, s70, v230
	v_fma_f32 v75, v228, s71, v230
	v_exp_f32_e32 v224, v106
	v_exp_f32_e32 v122, v122
	v_add_u32_e32 v78, v198, v226
	ds_read_b128 v[94:97], v78 offset:49152
	s_waitcnt lgkmcnt(3)
	v_mfma_f32_32x32x16_bf16 v[34:49], v[90:93], v[98:101], v[34:49]
	v_add_f32_e32 v254, v238, v254
	v_add_f32_e32 v254, v239, v254
	v_exp_f32_e32 v225, v107
	v_exp_f32_e32 v123, v123
	ds_read_b128 v[90:93], v78 offset:53248
	s_waitcnt lgkmcnt(3)
	v_mfma_f32_32x32x16_bf16 v[18:33], v[86:89], v[98:101], v[18:33]
	v_add_f32_e32 v254, v240, v254
	v_add_f32_e32 v254, v241, v254
	v_fma_f32 v76, v228, s72, v230
	v_fma_f32 v77, v228, s73, v230
	v_exp_f32_e32 v227, v108
	v_exp_f32_e32 v124, v124
	ds_read_b128 v[86:89], v78 offset:57344
	s_waitcnt lgkmcnt(3)
	v_mfma_f32_32x32x16_bf16 v[2:17], v[82:85], v[98:101], v[2:17]
	v_add_f32_e32 v254, v242, v254
	v_add_f32_e32 v254, v243, v254
	v_exp_f32_e32 v244, v109
	v_exp_f32_e32 v125, v125
	ds_read_b128 v[98:101], v78 offset:61440
	s_waitcnt lgkmcnt(3)
	v_mfma_f32_32x32x16_bf16 v[50:65], v[94:97], v[114:117], v[50:65]
	v_add_f32_e32 v254, v181, v254
	v_add_f32_e32 v254, v183, v254
	v_fma_f32 v78, v228, s74, v230
	v_fma_f32 v79, v228, s75, v230
	v_exp_f32_e32 v245, v110
	v_exp_f32_e32 v126, v126
	v_add_u32_e32 v80, v229, v149
	ds_read_b128 v[102:105], v80
	s_waitcnt lgkmcnt(3)
	v_mfma_f32_32x32x16_bf16 v[34:49], v[90:93], v[114:117], v[34:49]
	v_add_f32_e32 v254, v195, v254
	v_add_f32_e32 v254, v200, v254
	v_exp_f32_e32 v246, v111
	v_exp_f32_e32 v127, v127
	ds_read_b128 v[106:109], v80 offset:4096
	s_waitcnt lgkmcnt(3)
	v_mfma_f32_32x32x16_bf16 v[18:33], v[86:89], v[114:117], v[18:33]
	v_add_f32_e32 v254, v224, v254
	v_add_f32_e32 v254, v122, v254
	v_fma_f32 v80, v228, s76, v230
	v_fma_f32 v81, v228, s77, v230
	v_exp_f32_e32 v247, v112
	v_exp_f32_e32 v128, v128
	v_add_u32_e32 v110, v229, v208
	ds_read_b128 v[118:121], v110
	s_waitcnt lgkmcnt(3)
	v_mfma_f32_32x32x16_bf16 v[2:17], v[98:101], v[114:117], v[2:17]
	v_add_f32_e32 v254, v225, v254
	v_add_f32_e32 v254, v123, v254
	v_add_f32_e64 v82, v232, v66
	v_add_f32_e64 v83, v232, v67
	v_add_f32_e64 v96, v232, v80
	v_add_f32_e64 v97, v232, v81
	v_add_f32_e64 v94, v232, v78
	v_add_f32_e64 v95, v232, v79
	v_add_f32_e32 v92, v232, v76
	v_add_f32_e32 v93, v232, v77
	v_add_f32_e32 v90, v232, v74
	v_add_f32_e32 v91, v232, v75
	v_add_f32_e32 v88, v232, v72
	v_add_f32_e32 v89, v232, v73
	v_add_f32_e32 v86, v232, v70
	v_add_f32_e32 v87, v232, v71
	v_add_f32_e32 v84, v232, v68
	v_add_f32_e32 v85, v232, v69
	v_exp_f32_e32 v228, v113
	v_exp_f32_e32 v129, v129
	ds_read_b128 v[98:101], v110 offset:4096
	s_waitcnt lgkmcnt(3)
	v_mfma_f32_32x32x16_bf16 v[66:81], v[102:105], v[130:133], v[66:81]
	v_add_f32_e32 v254, v227, v254
	v_add_f32_e32 v254, v124, v254
	v_add_f32_e32 v254, v244, v254
	v_add_u32_e32 v110, v229, v209
	ds_read_b128 v[102:105], v110
	s_waitcnt lgkmcnt(3)
	v_mfma_f32_32x32x16_bf16 v[82:97], v[106:109], v[130:133], v[82:97]
	v_add_f32_e32 v254, v125, v254
	v_add_f32_e32 v254, v245, v254
	v_add_f32_e32 v254, v126, v254
	ds_read_b128 v[106:109], v110 offset:4096
	s_waitcnt lgkmcnt(3)
	v_mfma_f32_32x32x16_bf16 v[66:81], v[118:121], v[134:137], v[66:81]
	v_add_f32_e32 v254, v246, v254
	v_add_f32_e32 v254, v127, v254
	v_add_f32_e32 v254, v247, v254
	v_add_u32_e32 v114, v229, v226
	ds_read_b128 v[110:113], v114
	s_waitcnt lgkmcnt(3)
	v_mfma_f32_32x32x16_bf16 v[82:97], v[98:101], v[134:137], v[82:97]
	v_add_f32_e32 v254, v128, v254
	v_add_f32_e32 v254, v228, v254
	v_add_f32_e32 v254, v129, v254
	ds_read_b128 v[98:101], v114 offset:4096
	s_waitcnt lgkmcnt(3)
	v_mfma_f32_32x32x16_bf16 v[66:81], v[102:105], v[138:141], v[66:81]
	v_cvt_pk_bf16_f32 v114, v122, v123
	v_cvt_pk_bf16_f32 v115, v124, v125
	v_cvt_pk_bf16_f32 v116, v126, v127
	v_cvt_pk_bf16_f32 v117, v128, v129
	s_waitcnt lgkmcnt(2)
	v_mfma_f32_32x32x16_bf16 v[82:97], v[106:109], v[138:141], v[82:97]
	v_cvt_pk_bf16_f32 v106, v224, v225
	v_cvt_pk_bf16_f32 v107, v227, v244
	v_cvt_pk_bf16_f32 v108, v245, v246
	v_cvt_pk_bf16_f32 v109, v247, v228
	s_waitcnt lgkmcnt(1)
	v_mfma_f32_32x32x16_bf16 v[66:81], v[110:113], v[142:145], v[66:81]
	v_cvt_pk_bf16_f32 v110, v233, v235
	v_cvt_pk_bf16_f32 v111, v237, v239
	v_cvt_pk_bf16_f32 v112, v241, v243
	v_cvt_pk_bf16_f32 v113, v183, v200
	s_waitcnt lgkmcnt(0)
	v_mfma_f32_32x32x16_bf16 v[82:97], v[98:101], v[142:145], v[82:97]
	s_add_i32 s10, s4, 1
	s_cmp_lg_u32 s4, 2
	s_cselect_b32 s62, s10, 0
	s_add_i32 s4, s5, 1
	s_cmp_lg_u32 s5, 2
	s_cselect_b32 s10, s4, 0
	s_add_i32 s34, s34, 2
	v_add_f32_e32 v198, v179, v254
	v_cvt_pk_bf16_f32 v98, v231, v234
	v_cvt_pk_bf16_f32 v99, v236, v238
	v_cvt_pk_bf16_f32 v100, v240, v242
	v_cvt_pk_bf16_f32 v101, v181, v195
	s_cmp_ge_i32 s61, s48
	s_cbranch_scc1 .LBB0_473
	s_mov_b32 s60, s63
	s_add_i32 s61, s34, -2
	s_cmp_gt_i32 s61, s48
	s_mov_b64 s[4:5], -1
	s_cbranch_scc1 .LBB0_451
.LBB0_468:
	s_waitcnt vmcnt(4) lgkmcnt(0)
	s_barrier
	s_cmp_eq_u32 s100, 0
	s_cbranch_scc1 .Lattn_fair_0
	s_setprio 1

.LBB0_469:
	s_waitcnt vmcnt(2) lgkmcnt(0)
	s_barrier
	s_cmp_eq_u32 s100, 0
	s_cbranch_scc1 .Lattn_fair_1
	s_setprio 1
.Lattn_fair_1:
	s_andn2_b64 vcc, exec, s[2:3]
	s_cbranch_vccz .LBB0_453
	s_branch .LBB0_454

	.amdhsa_kernel _Z9hymba_fwd4Args
		.amdhsa_group_segment_fixed_size 0
		.amdhsa_private_segment_fixed_size 0
		.amdhsa_kernarg_size 376
		.amdhsa_user_sgpr_count 2
		.amdhsa_user_sgpr_dispatch_ptr 0
		.amdhsa_user_sgpr_queue_ptr 0
		.amdhsa_user_sgpr_kernarg_segment_ptr 1
		.amdhsa_user_sgpr_dispatch_id 0
		.amdhsa_user_sgpr_kernarg_preload_length 0
		.amdhsa_user_sgpr_kernarg_preload_offset 0
		.amdhsa_user_sgpr_private_segment_size 0
		.amdhsa_uses_dynamic_stack 0
		.amdhsa_enable_private_segment 0
		.amdhsa_system_sgpr_workgroup_id_x 1
		.amdhsa_system_sgpr_workgroup_id_y 0
		.amdhsa_system_sgpr_workgroup_id_z 0
		.amdhsa_system_sgpr_workgroup_info 0
		.amdhsa_system_vgpr_workitem_id 2
		.amdhsa_next_free_vgpr 256
		.amdhsa_next_free_sgpr 102
		.amdhsa_accum_offset 256
		.amdhsa_reserve_vcc 1
		.amdhsa_float_round_mode_32 0
		.amdhsa_float_round_mode_16_64 0
		.amdhsa_float_denorm_mode_32 3
		.amdhsa_float_denorm_mode_16_64 3
		.amdhsa_dx10_clamp 1
		.amdhsa_ieee_mode 1
		.amdhsa_fp16_overflow 0
		.amdhsa_tg_split 0
		.amdhsa_exception_fp_ieee_invalid_op 0
		.amdhsa_exception_fp_denorm_src 0
		.amdhsa_exception_fp_ieee_div_zero 0
		.amdhsa_exception_fp_ieee_overflow 0
		.amdhsa_exception_fp_ieee_underflow 0
		.amdhsa_exception_fp_ieee_inexact 0
		.amdhsa_exception_int_div_zero 0
	.end_amdhsa_kernel

amdhsa.kernels:
  - .agpr_count:     0
    .args:
      - .offset:         0
        .size:           120
        .value_kind:     by_value
      - .offset:         120
        .size:           4
        .value_kind:     hidden_block_count_x
      - .offset:         124
        .size:           4
        .value_kind:     hidden_block_count_y
      - .offset:         128
        .size:           4
        .value_kind:     hidden_block_count_z
      - .offset:         132
        .size:           2
        .value_kind:     hidden_group_size_x
      - .offset:         134
        .size:           2
        .value_kind:     hidden_group_size_y
      - .offset:         136
        .size:           2
        .value_kind:     hidden_group_size_z
      - .offset:         138
        .size:           2
        .value_kind:     hidden_remainder_x
      - .offset:         140
        .size:           2
        .value_kind:     hidden_remainder_y
      - .offset:         142
        .size:           2
        .value_kind:     hidden_remainder_z
      - .offset:         160
        .size:           8
        .value_kind:     hidden_global_offset_x
      - .offset:         168
        .size:           8
        .value_kind:     hidden_global_offset_y
      - .offset:         176
        .size:           8
        .value_kind:     hidden_global_offset_z
      - .offset:         184
        .size:           2
        .value_kind:     hidden_grid_dims
      - .offset:         208
        .size:           8
        .value_kind:     hidden_multigrid_sync_arg
      - .offset:         240
        .size:           4
        .value_kind:     hidden_dynamic_lds_size
    .group_segment_fixed_size: 0
    .kernarg_segment_align: 8
    .kernarg_segment_size: 376
    .language:       OpenCL C
    .language_version:
      - 2
      - 0
    .max_flat_workgroup_size: 512
    .name:           _Z9hymba_fwd4Args
    .private_segment_fixed_size: 0
    .sgpr_count:     108
    .sgpr_spill_count: 36
    .symbol:         _Z9hymba_fwd4Args.kd
    .uniform_work_group_size: 1
    .uses_dynamic_stack: false
    .vgpr_count:     256
    .vgpr_spill_count: 0
    .wavefront_size: 64
